# attnA items batch-major (16 query blocks of one (b,h) adjacent in queue) for K/V L2 locality
# speedup vs baseline: 1.0177x; 1.0177x over previous
; #define LAS __attribute__((address_space(3)))
; __device__ __forceinline__ void attnA_unit(const P2Ctx& C, int b, int h, int qb) {
;     LAS unsigned char* lds = C.lds; const int lane = C.lane, wid = C.wid, pf = C.pf;
;     const int comp = wid >> 2, qs = wid & 3, r32 = lane & 31, hi = lane >> 5;
;     const int q0 = qb * 128, trow0 = b * SEQ;
;     const int qpos = q0 + qs * 32 + r32; const size_t qrow = (size_t)(trow0 + qpos);
;     const int qcw = (q0 + qs * 32) >> 6, ntw = qcw + 1, NT = 2 * qb + 2;
;     const LAS float* lut = (const LAS float*)(lds + LUT_OFF) + h * 256;
;     const float lam = *(const LAS float*)(lds + LAM_OFF);
;     bf16x8 qf[4];
; #pragma unroll
;     for (int ds = 0; ds < 4; ++ds) qf[ds] = *(const bf16x8*)(C.Q + qrow * DM + h * 128 + comp * 64 + ds * 16 + hi * 8);
;     const int kkey = 8 * wid + (lane >> 3), kchs = (lane & 7) ^ ((kkey >> 1) & 7);
;     const bf16_t* ksrc = C.Kb + ((size_t)trow0 + kkey) * DM + h * 128 + kchs * 8;
;     const bf16_t* vsrc[2];
; #pragma unroll
;     for (int i = 0; i < 2; ++i) { const int p = 2 * wid + i, kg = p >> 1, cbv = 2 * (p & 1) + (lane >> 5), vkey = kg * 8 + ((lane >> 2) & 7), vch = cbv * 4 + (lane & 3);
;         vsrc[i] = C.Vb + ((size_t)trow0 + vkey) * DM + h * 128 + vch * 8; }
; __device__ __forceinline__ void p2_mixers(CArgs& a0, LAS unsigned char* lds, int tid, int lane, int wid, int rep) {
;     ...
;             else if ((it -= 16) < 128) { if (umask & 4) attnA_unit(C, it & 7, qx, 15 - (it >> 3)); }
.LBB0_572:
	s_andn2_b64 vcc, exec, s[6:7]
	s_cbranch_vccnz .LBB0_614
	s_sub_i32 s6, s37, 32
	s_lshr_b32 s11, s6, 4
	s_and_b32 s6, s6, 15
	s_sub_i32 s10, 15, s6
	s_lshr_b32 s8, s83, 2
	s_and_b32 s9, s83, 3
	s_lshl_b32 s12, s10, 1
	s_add_i32 s12, s12, 2
	s_lshr_b32 s6, s9, 1
	s_lshl_b32 s13, s10, 1
	s_add_i32 s13, s13, s6
	s_add_i32 s13, s13, 1
	s_lshl_b32 s22, s83, 10
	s_lshl_b32 s23, s83, 11
	s_add_i32 s23, s23, 0x4000
	s_lshl_b32 s6, s10, 7
	s_lshl_b32 s7, s9, 5
	s_add_i32 s15, s6, s7
	s_add_i32 s26, s15, 0xffffff01
	s_mov_b32 s25, 0
	v_and_b32_e32 v100, 31, v219
	v_lshrrev_b32_e32 v101, 5, v219
	s_load_dwordx2 s[20:21], s[62:63], 0x80
	v_lshlrev_b32_e32 v107, 4, v196
	s_waitcnt lgkmcnt(0)
	v_cmp_gt_u32_e32 vcc, 32, v196
	s_and_saveexec_b64 s[6:7], vcc
	global_load_dwordx4 v[108:111], v107, s[20:21]
	s_or_b64 exec, exec, s[6:7]
	s_lshl_b32 s6, s11, 11
	s_add_i32 s6, s6, s15
	s_lshl_b32 s6, s6, 11
	s_lshl_b32 s7, s81, 1
	s_add_i32 s6, s6, s7
	s_lshl_b32 s7, s8, 7
	s_add_i32 s6, s6, s7
	s_add_u32 s20, s76, s6
	s_addc_u32 s21, s77, 0
	v_lshlrev_b32_e32 v102, 11, v100
	v_lshl_add_u32 v102, v101, 4, v102
	global_load_dwordx4 v[164:167], v102, s[20:21]
	global_load_dwordx4 v[168:171], v102, s[20:21] offset:32
	global_load_dwordx4 v[172:175], v102, s[20:21] offset:64
	global_load_dwordx4 v[176:179], v102, s[20:21] offset:96
	s_lshl_b32 s6, s11, 22
	s_lshl_b32 s7, s81, 1
	s_add_i32 s6, s6, s7
	s_add_u32 s16, s72, s6
	s_addc_u32 s17, s73, 0
	s_add_u32 s18, s74, s6
	s_addc_u32 s19, s75, 0
	s_mov_b32 s24, 0
	v_lshrrev_b32_e32 v103, 3, v219
	s_lshl_b32 s6, s83, 3
	v_add_u32_e32 v103, s6, v103
	v_bfe_u32 v104, v103, 1, 3
	v_and_b32_e32 v105, 7, v219
	v_xor_b32_e32 v104, v104, v105
	v_lshlrev_b32_e32 v104, 4, v104
	v_lshl_add_u32 v197, v103, 11, v104
	v_bfe_u32 v103, v219, 2, 3
	v_add_u32_e32 v103, s6, v103
	v_and_b32_e32 v104, 3, v219
	v_lshlrev_b32_e32 v104, 4, v104
	v_lshl_add_u32 v104, v101, 6, v104
	v_lshl_add_u32 v198, v103, 11, v104
	s_and_b32 s6, s24, 3
	s_lshl_b32 s6, s6, 15
	s_add_i32 s7, s6, s22
	s_mov_b32 m0, s7
	s_add_u32 s20, s16, 0x80
	s_addc_u32 s21, s17, 0
	s_add_i32 s29, s6, s23
	global_load_lds_dwordx4 v197, s[16:17]
	s_add_i32 m0, s7, 0x2000
	s_add_u32 s16, s16, 0x20000
	s_addc_u32 s17, s17, 0
	s_nop 0
	global_load_lds_dwordx4 v197, s[20:21]
	s_mov_b32 m0, s29
	s_add_u32 s20, s18, 0x80
	s_addc_u32 s21, s19, 0
	s_nop 0
	global_load_lds_dwordx4 v198, s[18:19]
	s_add_i32 m0, s29, 0x400
	s_add_u32 s18, s18, 0x20000
	s_addc_u32 s19, s19, 0
	s_add_i32 s24, s24, 1
	global_load_lds_dwordx4 v198, s[20:21]
	s_and_b32 s6, s24, 3
	s_lshl_b32 s6, s6, 15
	s_add_i32 s7, s6, s22
	s_mov_b32 m0, s7
	s_add_u32 s20, s16, 0x80
	s_addc_u32 s21, s17, 0
	s_add_i32 s29, s6, s23
	global_load_lds_dwordx4 v197, s[16:17]
	s_add_i32 m0, s7, 0x2000
	s_add_u32 s16, s16, 0x20000
	s_addc_u32 s17, s17, 0
	s_nop 0
	global_load_lds_dwordx4 v197, s[20:21]
	s_mov_b32 m0, s29
	s_add_u32 s20, s18, 0x80
	s_addc_u32 s21, s19, 0
	s_nop 0
	global_load_lds_dwordx4 v198, s[18:19]
	s_add_i32 m0, s29, 0x400
	s_add_u32 s18, s18, 0x20000
	s_addc_u32 s19, s19, 0
	s_add_i32 s24, s24, 1
	global_load_lds_dwordx4 v198, s[20:21]
	v_bfe_u32 v103, v100, 1, 3
	v_lshlrev_b32_e32 v104, 7, v100
	s_lshl_b32 s6, s8, 13
	v_add_u32_e32 v104, s6, v104
	v_or_b32_e32 v105, 0, v101
	v_xor_b32_e32 v105, v105, v103
	v_lshl_add_u32 v200, v105, 4, v104
	v_or_b32_e32 v105, 2, v101
	v_xor_b32_e32 v105, v105, v103
	v_lshl_add_u32 v201, v105, 4, v104
	v_or_b32_e32 v105, 4, v101
	v_xor_b32_e32 v105, v105, v103
	v_lshl_add_u32 v202, v105, 4, v104
	v_or_b32_e32 v105, 6, v101
	v_xor_b32_e32 v105, v105, v103
	v_lshl_add_u32 v203, v105, 4, v104
	v_bfe_u32 v103, v219, 2, 2
	v_lshl_add_u32 v103, v101, 2, v103
	v_lshlrev_b32_e32 v103, 6, v103
	v_bfe_u32 v104, v219, 4, 1
	v_lshl_add_u32 v103, v104, 5, v103
	v_and_b32_e32 v104, 3, v219
	v_lshl_add_u32 v103, v104, 3, v103
	v_add_u32_e32 v204, 0x4000, v103
	s_sub_i32 s6, 0x120, s15
	s_lshl_b32 s6, s6, 2
	s_add_i32 s6, s6, 0x22400
	v_lshlrev_b32_e32 v103, 4, v101
	v_lshlrev_b32_e32 v104, 2, v100
	v_sub_u32_e32 v103, v103, v104
	v_add_u32_e32 v236, s6, v103
	v_cmp_gt_u32_e32 vcc, 0x160, v196
	s_and_saveexec_b64 s[6:7], vcc
	s_cbranch_execz .LaA_padskip_1
	v_subrev_u32_e32 v103, 0x60, v196
	v_max_i32_e32 v104, 0, v103
	v_lshl_add_u32 v104, v104, 2, s42
	ds_read_b32 v105, v104
	v_cmp_gt_i32_e32 vcc, 0, v103
	v_mov_b32_e32 v106, 0x22400
	v_lshl_add_u32 v104, v196, 2, v106
	s_waitcnt lgkmcnt(0)
	v_cndmask_b32_e64 v105, v105, 0, vcc
	ds_write_b32 v104, v105
